# stack2: + SALU-only wave LDS base in 8x4 steady heads + T21 widened stores in attn_d epilogue
# baseline (speedup 1.0000x reference)
; #define LDB_(dst, ks) _Pragma("unroll") for (int n = 0; n < 4; ++n) dst[n] = *(const bf16x8*)(sB + b_off + n * 2048 + (ks) * 1024)
; #define LDA_(dst, ks, h) _Pragma("unroll") for (int m = 0; m < 4; ++m) dst[m] = *(const bf16x8*)(sA + a_off + ((h) * 4 + m) * 2048 + (ks) * 1024)
; #define MMA_(A, B, h) _Pragma("unroll") for (int m = 0; m < 4; ++m) _Pragma("unroll") for (int n = 0; n < 4; ++n) \
;       acc[(h) * 4 + m][n] = SWAP ? MFMA16(B[n], A[m], acc[(h) * 4 + m][n]) : MFMA16(A[m], B[n], acc[(h) * 4 + m][n])
; template <int MF, int NF, bool SWAP = true>
; DI void gemm_main(f32x4 (&acc)[MF][NF], const u16* __restrict__ Ab, int lda, const u16* __restrict__ Bb, int ldb,
;                   int K, char* shm) {
;     ...
;   for (int t = 0; t < nt; ++t) {
;     const int cur = RING3 ? cur3 : (t & 1);
;     if constexpr (RING3) {
;       if (t + 2 < nt) G_STAGE(nxt3, t + 2);
;     } else {
;       if (t + 1 < nt) G_STAGE(cur ^ 1, t + 1);
;     }
;     const char* sA = shm + cur * STAGE;
;     const char* sB = sA + TILE_A;
;     if constexpr (MF == 8 && NF == 4) {
;       bf16x8 B0[4], B1[4], A0[4], A1[4], A2[4], A3[4];
;     ...
;       LDB_(B0, 0); LDA_(A0, 0, 0);
;       LDA_(A1, 0, 1); MMA_(A0, B0, 0);
;       LDB_(B1, 1); LDA_(A2, 1, 0); MMA_(A1, B0, 1);
;       LDA_(A3, 1, 1); MMA_(A2, B1, 0);
;       MMA_(A3, B1, 1);
.LBB0_146:
	s_and_b32 s19, s17, 0x10000
	s_cmp_gt_u32 s13, 14
	s_cbranch_scc1 .Lg_rot146_last
	s_cmp_eq_u32 s13, 0
	s_cbranch_scc1 .Lg_rot146_first
	v_mfma_f32_16x16x32_bf16 v[60:63], v[186:189], v[190:193], v[60:63]
	s_xor_b32 s20, s19, 0x10000
	v_mfma_f32_16x16x32_bf16 v[56:59], v[194:197], v[190:193], v[56:59]
	s_add_u32 s20, s20, s26
	s_add_u32 m0, s20, 0x0
	v_mfma_f32_16x16x32_bf16 v[52:55], v[198:201], v[190:193], v[52:55]
	global_load_lds_dwordx4 v251, s[98:99]
	s_add_u32 m0, s20, 0x2000
	v_mfma_f32_16x16x32_bf16 v[48:51], v[212:215], v[190:193], v[48:51]
	global_load_lds_dwordx4 v250, s[98:99]
	s_add_u32 m0, s20, 0x4000
	v_mfma_f32_16x16x32_bf16 v[44:47], v[186:189], v[216:219], v[44:47]
	global_load_lds_dwordx4 v249, s[98:99]
	s_add_u32 m0, s20, 0x6000
	v_mfma_f32_16x16x32_bf16 v[40:43], v[194:197], v[216:219], v[40:43]
	global_load_lds_dwordx4 v248, s[98:99]
	s_add_u32 m0, s20, 0x8000
	v_mfma_f32_16x16x32_bf16 v[36:39], v[198:201], v[216:219], v[36:39]
	global_load_lds_dwordx4 v247, s[100:101]
	s_add_u32 m0, s20, 0xa000
	v_mfma_f32_16x16x32_bf16 v[32:35], v[212:215], v[216:219], v[32:35]
	global_load_lds_dwordx4 v246, s[100:101]
	s_add_u32 m0, s20, 0xc000
	v_mfma_f32_16x16x32_bf16 v[28:31], v[186:189], v[220:223], v[28:31]
	global_load_lds_dwordx4 v245, s[100:101]
	s_add_u32 m0, s20, 0xe000
	v_mfma_f32_16x16x32_bf16 v[24:27], v[194:197], v[220:223], v[24:27]
	global_load_lds_dwordx4 v244, s[100:101]
	v_mfma_f32_16x16x32_bf16 v[20:23], v[198:201], v[220:223], v[20:23]
	s_add_u32 s98, s98, 0x80
	s_addc_u32 s99, s99, 0
	s_add_u32 s100, s100, 0x80
	s_addc_u32 s101, s101, 0
	v_add_u32_e32 v137, s19, v132
	v_add_u32_e32 v178, v137, v131
	ds_read_b128 v[138:141], v178 offset:32768
	ds_read_b128 v[142:145], v178 offset:34816
	ds_read_b128 v[146:149], v178 offset:36864
	ds_read_b128 v[150:153], v178 offset:38912
	v_add_u32_e32 v137, v137, v129
	ds_read_b128 v[154:157], v137
	ds_read_b128 v[158:161], v137 offset:2048
	ds_read_b128 v[162:165], v137 offset:4096
	ds_read_b128 v[166:169], v137 offset:6144
	ds_read_b128 v[170:173], v137 offset:8192
	v_mfma_f32_16x16x32_bf16 v[16:19], v[212:215], v[220:223], v[16:19]
	v_mfma_f32_16x16x32_bf16 v[12:15], v[186:189], v[224:227], v[12:15]
	v_mfma_f32_16x16x32_bf16 v[8:11], v[194:197], v[224:227], v[8:11]
	v_mfma_f32_16x16x32_bf16 v[4:7], v[198:201], v[224:227], v[4:7]
	v_mfma_f32_16x16x32_bf16 v[0:3], v[212:215], v[224:227], v[0:3]
	s_branch .Lg_rot146_main
.Lg_rot146_first:
	v_add_u32_e32 v174, s11, v136
	s_xor_b32 s20, s19, 0x10000
	v_add_u32_e32 v176, 64, v174
	v_add_u32_e32 v179, s20, v128
	v_ashrrev_i32_e32 v177, 31, v176
	v_lshlrev_b64 v[176:177], 1, v[176:177]
	v_readfirstlane_b32 s20, v179
	v_lshl_add_u64 v[180:181], s[0:1], 0, v[176:177]
	s_mov_b32 m0, s20
	v_add_u32_e32 v182, 0x2000, v179
	global_load_lds_dwordx4 v[180:181], off
	v_subrev_u32_e32 v251, s0, v180
	v_add_u32_e32 v180, 0x10040, v174
	v_ashrrev_i32_e32 v181, 31, v180
	v_lshlrev_b64 v[180:181], 1, v[180:181]
	v_readfirstlane_b32 s20, v182
	v_lshl_add_u64 v[184:185], s[0:1], 0, v[180:181]
	s_mov_b32 m0, s20
	v_add_u32_e32 v175, 0x4000, v179
	global_load_lds_dwordx4 v[184:185], off
	v_subrev_u32_e32 v250, s0, v184
	v_add_u32_e32 v184, 0x20040, v174
	v_ashrrev_i32_e32 v185, 31, v184
	v_lshlrev_b64 v[184:185], 1, v[184:185]
	v_readfirstlane_b32 s20, v175
	v_lshl_add_u64 v[182:183], s[0:1], 0, v[184:185]
	s_mov_b32 m0, s20
	v_add_u32_e32 v211, 0x6000, v179
	global_load_lds_dwordx4 v[182:183], off
	v_subrev_u32_e32 v249, s0, v182
	v_add_u32_e32 v182, 0x30040, v174
	v_ashrrev_i32_e32 v183, 31, v182
	v_lshlrev_b64 v[182:183], 1, v[182:183]
	v_readfirstlane_b32 s20, v211
	v_lshl_add_u64 v[174:175], s[0:1], 0, v[182:183]
	s_mov_b32 m0, s20
	v_lshl_add_u64 v[176:177], s[4:5], 0, v[176:177]
	global_load_lds_dwordx4 v[174:175], off
	v_subrev_u32_e32 v248, s0, v174
	v_add_u32_e32 v174, 0x8000, v179
	s_nop 0
	v_readfirstlane_b32 s20, v174
	s_mov_b32 m0, s20
	s_nop 0
	global_load_lds_dwordx4 v[176:177], off
	v_subrev_u32_e32 v247, s4, v176
	v_lshl_add_u64 v[176:177], s[4:5], 0, v[180:181]
	v_add_u32_e32 v180, 0xa000, v179
	s_nop 0
	v_readfirstlane_b32 s20, v180
	v_add_u32_e32 v180, 0xc000, v179
	s_mov_b32 m0, s20
	v_readfirstlane_b32 s20, v180
	v_add_u32_e32 v179, 0xe000, v179
	global_load_lds_dwordx4 v[176:177], off
	v_subrev_u32_e32 v246, s4, v176
	v_lshl_add_u64 v[176:177], s[4:5], 0, v[184:185]
	s_mov_b32 m0, s20
	v_readfirstlane_b32 s20, v179
	global_load_lds_dwordx4 v[176:177], off
	v_subrev_u32_e32 v245, s4, v176
	v_lshl_add_u64 v[176:177], s[4:5], 0, v[182:183]
	s_mov_b32 m0, s20
	s_nop 0
	global_load_lds_dwordx4 v[176:177], off
	v_subrev_u32_e32 v244, s4, v176
	s_add_u32 s98, s0, 0x80
	s_addc_u32 s99, s1, 0
	s_add_u32 s100, s4, 0x80
	s_addc_u32 s101, s5, 0
	v_readfirstlane_b32 s26, v128
	s_nop 0
	s_nop 0
	v_add_u32_e32 v137, s19, v132
	v_add_u32_e32 v178, v137, v131
	ds_read_b128 v[138:141], v178 offset:32768
	ds_read_b128 v[142:145], v178 offset:34816
	ds_read_b128 v[146:149], v178 offset:36864
	ds_read_b128 v[150:153], v178 offset:38912
	v_add_u32_e32 v137, v137, v129
	ds_read_b128 v[154:157], v137
	ds_read_b128 v[158:161], v137 offset:2048
	ds_read_b128 v[162:165], v137 offset:4096
	ds_read_b128 v[166:169], v137 offset:6144
	ds_read_b128 v[170:173], v137 offset:8192
	s_branch .Lg_rot146_main

; #define LDB_(dst, ks) _Pragma("unroll") for (int n = 0; n < 4; ++n) dst[n] = *(const bf16x8*)(sB + b_off + n * 2048 + (ks) * 1024)
; #define LDA_(dst, ks, h) _Pragma("unroll") for (int m = 0; m < 4; ++m) dst[m] = *(const bf16x8*)(sA + a_off + ((h) * 4 + m) * 2048 + (ks) * 1024)
; #define MMA_(A, B, h) _Pragma("unroll") for (int m = 0; m < 4; ++m) _Pragma("unroll") for (int n = 0; n < 4; ++n) \
;       acc[(h) * 4 + m][n] = SWAP ? MFMA16(B[n], A[m], acc[(h) * 4 + m][n]) : MFMA16(A[m], B[n], acc[(h) * 4 + m][n])
; template <int MF, int NF, bool SWAP = true>
; DI void gemm_main(f32x4 (&acc)[MF][NF], const u16* __restrict__ Ab, int lda, const u16* __restrict__ Bb, int ldb,
;                   int K, char* shm) {
;     ...
;   for (int t = 0; t < nt; ++t) {
;     const int cur = RING3 ? cur3 : (t & 1);
;     if constexpr (RING3) {
;       if (t + 2 < nt) G_STAGE(nxt3, t + 2);
;     } else {
;       if (t + 1 < nt) G_STAGE(cur ^ 1, t + 1);
;     }
;     const char* sA = shm + cur * STAGE;
;     const char* sB = sA + TILE_A;
;     if constexpr (MF == 8 && NF == 4) {
;       bf16x8 B0[4], B1[4], A0[4], A1[4], A2[4], A3[4];
;     ...
;       LDB_(B0, 0); LDA_(A0, 0, 0);
;       LDA_(A1, 0, 1); MMA_(A0, B0, 0);
;       LDB_(B1, 1); LDA_(A2, 1, 0); MMA_(A1, B0, 1);
;       LDA_(A3, 1, 1); MMA_(A2, B1, 0);
;       MMA_(A3, B1, 1);
.LBB0_244:
	s_and_b32 s18, s15, 0x10000
	s_cmp_gt_u32 s17, 14
	s_cbranch_scc1 .Lg_rot244_last
	s_cmp_eq_u32 s17, 0
	s_cbranch_scc1 .Lg_rot244_first
	v_mfma_f32_16x16x32_bf16 v[60:63], v[188:191], v[192:195], v[60:63]
	s_xor_b32 s19, s18, 0x10000
	v_mfma_f32_16x16x32_bf16 v[56:59], v[196:199], v[192:195], v[56:59]
	s_add_u32 s19, s19, s26
	s_add_u32 m0, s19, 0x0
	v_mfma_f32_16x16x32_bf16 v[52:55], v[212:215], v[192:195], v[52:55]
	global_load_lds_dwordx4 v251, s[98:99]
	s_add_u32 m0, s19, 0x2000
	v_mfma_f32_16x16x32_bf16 v[48:51], v[216:219], v[192:195], v[48:51]
	global_load_lds_dwordx4 v250, s[98:99]
	s_add_u32 m0, s19, 0x4000
	v_mfma_f32_16x16x32_bf16 v[44:47], v[188:191], v[220:223], v[44:47]
	global_load_lds_dwordx4 v249, s[98:99]
	s_add_u32 m0, s19, 0x6000
	v_mfma_f32_16x16x32_bf16 v[40:43], v[196:199], v[220:223], v[40:43]
	global_load_lds_dwordx4 v248, s[98:99]
	s_add_u32 m0, s19, 0x8000
	v_mfma_f32_16x16x32_bf16 v[36:39], v[212:215], v[220:223], v[36:39]
	global_load_lds_dwordx4 v247, s[100:101]
	s_add_u32 m0, s19, 0xa000
	v_mfma_f32_16x16x32_bf16 v[32:35], v[216:219], v[220:223], v[32:35]
	global_load_lds_dwordx4 v246, s[100:101]
	s_add_u32 m0, s19, 0xc000
	v_mfma_f32_16x16x32_bf16 v[28:31], v[188:191], v[224:227], v[28:31]
	global_load_lds_dwordx4 v245, s[100:101]
	s_add_u32 m0, s19, 0xe000
	v_mfma_f32_16x16x32_bf16 v[24:27], v[196:199], v[224:227], v[24:27]
	global_load_lds_dwordx4 v244, s[100:101]
	v_mfma_f32_16x16x32_bf16 v[20:23], v[212:215], v[224:227], v[20:23]
	s_add_u32 s98, s98, 0x80
	s_addc_u32 s99, s99, 0
	s_add_u32 s100, s100, 0x80
	s_addc_u32 s101, s101, 0
	v_add_u32_e32 v154, s18, v136
	v_add_u32_e32 v178, v154, v132
	ds_read_b128 v[138:141], v178 offset:32768
	ds_read_b128 v[142:145], v178 offset:34816
	ds_read_b128 v[146:149], v178 offset:36864
	ds_read_b128 v[150:153], v178 offset:38912
	v_add_u32_e32 v186, v154, v129
	ds_read_b128 v[154:157], v186
	ds_read_b128 v[158:161], v186 offset:2048
	ds_read_b128 v[162:165], v186 offset:4096
	ds_read_b128 v[166:169], v186 offset:6144
	ds_read_b128 v[170:173], v186 offset:8192
	v_mfma_f32_16x16x32_bf16 v[16:19], v[216:219], v[224:227], v[16:19]
	v_mfma_f32_16x16x32_bf16 v[12:15], v[188:191], v[228:231], v[12:15]
	v_mfma_f32_16x16x32_bf16 v[8:11], v[196:199], v[228:231], v[8:11]
	v_mfma_f32_16x16x32_bf16 v[4:7], v[212:215], v[228:231], v[4:7]
	v_mfma_f32_16x16x32_bf16 v[0:3], v[216:219], v[228:231], v[0:3]
	s_branch .Lg_rot244_main
.Lg_rot244_first:
	v_add_u32_e32 v174, s16, v137
	s_xor_b32 s19, s18, 0x10000
	v_add_u32_e32 v176, 64, v174
	v_add_u32_e32 v179, s19, v128
	v_ashrrev_i32_e32 v177, 31, v176
	v_lshlrev_b64 v[176:177], 1, v[176:177]
	v_readfirstlane_b32 s19, v179
	v_lshl_add_u64 v[180:181], s[6:7], 0, v[176:177]
	s_mov_b32 m0, s19
	v_add_u32_e32 v182, 0x2000, v179
	global_load_lds_dwordx4 v[180:181], off
	v_subrev_u32_e32 v251, s6, v180
	v_add_u32_e32 v180, 0x10040, v174
	v_ashrrev_i32_e32 v181, 31, v180
	v_lshlrev_b64 v[180:181], 1, v[180:181]
	v_readfirstlane_b32 s19, v182
	v_lshl_add_u64 v[184:185], s[6:7], 0, v[180:181]
	s_mov_b32 m0, s19
	v_add_u32_e32 v175, 0x4000, v179
	global_load_lds_dwordx4 v[184:185], off
	v_subrev_u32_e32 v250, s6, v184
	v_add_u32_e32 v184, 0x20040, v174
	v_ashrrev_i32_e32 v185, 31, v184
	v_lshlrev_b64 v[184:185], 1, v[184:185]
	v_readfirstlane_b32 s19, v175
	v_lshl_add_u64 v[182:183], s[6:7], 0, v[184:185]
	s_mov_b32 m0, s19
	v_add_u32_e32 v187, 0x6000, v179
	global_load_lds_dwordx4 v[182:183], off
	v_subrev_u32_e32 v249, s6, v182
	v_add_u32_e32 v182, 0x30040, v174
	v_ashrrev_i32_e32 v183, 31, v182
	v_lshlrev_b64 v[182:183], 1, v[182:183]
	v_readfirstlane_b32 s19, v187
	v_lshl_add_u64 v[174:175], s[6:7], 0, v[182:183]
	s_mov_b32 m0, s19
	v_lshl_add_u64 v[176:177], s[0:1], 0, v[176:177]
	global_load_lds_dwordx4 v[174:175], off
	v_subrev_u32_e32 v248, s6, v174
	v_add_u32_e32 v174, 0x8000, v179
	s_nop 0
	v_readfirstlane_b32 s19, v174
	s_mov_b32 m0, s19
	s_nop 0
	global_load_lds_dwordx4 v[176:177], off
	v_subrev_u32_e32 v247, s0, v176
	v_lshl_add_u64 v[176:177], s[0:1], 0, v[180:181]
	v_add_u32_e32 v180, 0xa000, v179
	s_nop 0
	v_readfirstlane_b32 s19, v180
	v_add_u32_e32 v180, 0xc000, v179
	s_mov_b32 m0, s19
	v_readfirstlane_b32 s19, v180
	v_add_u32_e32 v180, 0xe000, v179
	global_load_lds_dwordx4 v[176:177], off
	v_subrev_u32_e32 v246, s0, v176
	v_lshl_add_u64 v[176:177], s[0:1], 0, v[184:185]
	s_mov_b32 m0, s19
	v_readfirstlane_b32 s19, v180
	global_load_lds_dwordx4 v[176:177], off
	v_subrev_u32_e32 v245, s0, v176
	v_lshl_add_u64 v[176:177], s[0:1], 0, v[182:183]
	s_mov_b32 m0, s19
	s_nop 0
	global_load_lds_dwordx4 v[176:177], off
	v_subrev_u32_e32 v244, s0, v176
	s_add_u32 s98, s6, 0x80
	s_addc_u32 s99, s7, 0
	s_add_u32 s100, s0, 0x80
	s_addc_u32 s101, s1, 0
	v_readfirstlane_b32 s26, v128
	s_nop 0
	s_nop 0
	v_add_u32_e32 v154, s18, v136
	v_add_u32_e32 v178, v154, v132
	ds_read_b128 v[138:141], v178 offset:32768
	ds_read_b128 v[142:145], v178 offset:34816
	ds_read_b128 v[146:149], v178 offset:36864
	ds_read_b128 v[150:153], v178 offset:38912
	v_add_u32_e32 v186, v154, v129
	ds_read_b128 v[154:157], v186
	ds_read_b128 v[158:161], v186 offset:2048
	ds_read_b128 v[162:165], v186 offset:4096
	ds_read_b128 v[166:169], v186 offset:6144
	ds_read_b128 v[170:173], v186 offset:8192
	s_branch .Lg_rot244_main

; #define LDB_(dst, ks) _Pragma("unroll") for (int n = 0; n < 4; ++n) dst[n] = *(const bf16x8*)(sB + b_off + n * 2048 + (ks) * 1024)
; #define LDA_(dst, ks, h) _Pragma("unroll") for (int m = 0; m < 4; ++m) dst[m] = *(const bf16x8*)(sA + a_off + ((h) * 4 + m) * 2048 + (ks) * 1024)
; #define MMA_(A, B, h) _Pragma("unroll") for (int m = 0; m < 4; ++m) _Pragma("unroll") for (int n = 0; n < 4; ++n) \
;       acc[(h) * 4 + m][n] = SWAP ? MFMA16(B[n], A[m], acc[(h) * 4 + m][n]) : MFMA16(A[m], B[n], acc[(h) * 4 + m][n])
; template <int MF, int NF, bool SWAP = true>
; DI void gemm_main(f32x4 (&acc)[MF][NF], const u16* __restrict__ Ab, int lda, const u16* __restrict__ Bb, int ldb,
;                   int K, char* shm) {
;     ...
;   for (int t = 0; t < nt; ++t) {
;     const int cur = RING3 ? cur3 : (t & 1);
;     if constexpr (RING3) {
;       if (t + 2 < nt) G_STAGE(nxt3, t + 2);
;     } else {
;       if (t + 1 < nt) G_STAGE(cur ^ 1, t + 1);
;     }
;     const char* sA = shm + cur * STAGE;
;     const char* sB = sA + TILE_A;
;     if constexpr (MF == 8 && NF == 4) {
;       bf16x8 B0[4], B1[4], A0[4], A1[4], A2[4], A3[4];
;     ...
;       LDB_(B0, 0); LDA_(A0, 0, 0);
;       LDA_(A1, 0, 1); MMA_(A0, B0, 0);
;       LDB_(B1, 1); LDA_(A2, 1, 0); MMA_(A1, B0, 1);
;       LDA_(A3, 1, 1); MMA_(A2, B1, 0);
;       MMA_(A3, B1, 1);
.LBB0_314:
	s_and_b32 s16, s5, 0x10000
	s_cmp_gt_u32 s15, 14
	s_cbranch_scc1 .Lg_rot314_last
	s_cmp_eq_u32 s15, 0
	s_cbranch_scc1 .Lg_rot314_first
	v_mfma_f32_16x16x32_bf16 v[60:63], v[188:191], v[192:195], v[60:63]
	s_xor_b32 s17, s16, 0x10000
	v_mfma_f32_16x16x32_bf16 v[56:59], v[188:191], v[196:199], v[56:59]
	s_add_u32 s17, s17, s26
	s_add_u32 m0, s17, 0x0
	v_mfma_f32_16x16x32_bf16 v[52:55], v[188:191], v[212:215], v[52:55]
	global_load_lds_dwordx4 v251, s[98:99]
	s_add_u32 m0, s17, 0x2000
	v_mfma_f32_16x16x32_bf16 v[48:51], v[188:191], v[216:219], v[48:51]
	global_load_lds_dwordx4 v250, s[98:99]
	s_add_u32 m0, s17, 0x4000
	v_mfma_f32_16x16x32_bf16 v[44:47], v[220:223], v[192:195], v[44:47]
	global_load_lds_dwordx4 v249, s[98:99]
	s_add_u32 m0, s17, 0x6000
	v_mfma_f32_16x16x32_bf16 v[40:43], v[220:223], v[196:199], v[40:43]
	global_load_lds_dwordx4 v248, s[98:99]
	s_add_u32 m0, s17, 0x8000
	v_mfma_f32_16x16x32_bf16 v[36:39], v[220:223], v[212:215], v[36:39]
	global_load_lds_dwordx4 v247, s[100:101]
	s_add_u32 m0, s17, 0xa000
	v_mfma_f32_16x16x32_bf16 v[32:35], v[220:223], v[216:219], v[32:35]
	global_load_lds_dwordx4 v246, s[100:101]
	s_add_u32 m0, s17, 0xc000
	v_mfma_f32_16x16x32_bf16 v[28:31], v[224:227], v[192:195], v[28:31]
	global_load_lds_dwordx4 v245, s[100:101]
	s_add_u32 m0, s17, 0xe000
	v_mfma_f32_16x16x32_bf16 v[24:27], v[224:227], v[196:199], v[24:27]
	global_load_lds_dwordx4 v244, s[100:101]
	v_mfma_f32_16x16x32_bf16 v[20:23], v[224:227], v[212:215], v[20:23]
	s_add_u32 s98, s98, 0x80
	s_addc_u32 s99, s99, 0
	s_add_u32 s100, s100, 0x80
	s_addc_u32 s101, s101, 0
	v_add_u32_e32 v138, s16, v136
	v_add_u32_e32 v186, v138, v129
	v_add_u32_e32 v178, v138, v132
	ds_read_b128 v[138:141], v186
	ds_read_b128 v[158:161], v186 offset:2048
	ds_read_b128 v[142:145], v178 offset:32768
	ds_read_b128 v[146:149], v178 offset:34816
	ds_read_b128 v[150:153], v178 offset:36864
	ds_read_b128 v[154:157], v178 offset:38912
	ds_read_b128 v[162:165], v186 offset:4096
	ds_read_b128 v[166:169], v186 offset:6144
	ds_read_b128 v[170:173], v186 offset:8192
	v_mfma_f32_16x16x32_bf16 v[16:19], v[224:227], v[216:219], v[16:19]
	v_mfma_f32_16x16x32_bf16 v[12:15], v[228:231], v[192:195], v[12:15]
	v_mfma_f32_16x16x32_bf16 v[4:7], v[228:231], v[196:199], v[4:7]
	v_mfma_f32_16x16x32_bf16 v[0:3], v[228:231], v[212:215], v[0:3]
	v_mfma_f32_16x16x32_bf16 v[8:11], v[228:231], v[216:219], v[8:11]
	s_branch .Lg_rot314_main
.Lg_rot314_first:
	v_add_u32_e32 v174, s13, v137
	s_xor_b32 s17, s16, 0x10000
	v_add_u32_e32 v176, 64, v174
	v_add_u32_e32 v179, s17, v128
	v_ashrrev_i32_e32 v177, 31, v176
	v_lshlrev_b64 v[176:177], 1, v[176:177]
	v_readfirstlane_b32 s17, v179
	v_lshl_add_u64 v[180:181], s[6:7], 0, v[176:177]
	s_mov_b32 m0, s17
	v_add_u32_e32 v182, 0x2000, v179
	global_load_lds_dwordx4 v[180:181], off
	v_subrev_u32_e32 v251, s6, v180
	v_add_u32_e32 v180, 0x10040, v174
	v_ashrrev_i32_e32 v181, 31, v180
	v_lshlrev_b64 v[180:181], 1, v[180:181]
	v_readfirstlane_b32 s17, v182
	v_lshl_add_u64 v[184:185], s[6:7], 0, v[180:181]
	s_mov_b32 m0, s17
	v_add_u32_e32 v175, 0x4000, v179
	global_load_lds_dwordx4 v[184:185], off
	v_subrev_u32_e32 v250, s6, v184
	v_add_u32_e32 v184, 0x20040, v174
	v_ashrrev_i32_e32 v185, 31, v184
	v_lshlrev_b64 v[184:185], 1, v[184:185]
	v_readfirstlane_b32 s17, v175
	v_lshl_add_u64 v[182:183], s[6:7], 0, v[184:185]
	s_mov_b32 m0, s17
	v_add_u32_e32 v187, 0x6000, v179
	global_load_lds_dwordx4 v[182:183], off
	v_subrev_u32_e32 v249, s6, v182
	v_add_u32_e32 v182, 0x30040, v174
	v_ashrrev_i32_e32 v183, 31, v182
	v_lshlrev_b64 v[182:183], 1, v[182:183]
	v_readfirstlane_b32 s17, v187
	v_lshl_add_u64 v[174:175], s[6:7], 0, v[182:183]
	s_mov_b32 m0, s17
	v_lshl_add_u64 v[176:177], s[0:1], 0, v[176:177]
	global_load_lds_dwordx4 v[174:175], off
	v_subrev_u32_e32 v248, s6, v174
	v_add_u32_e32 v174, 0x8000, v179
	s_nop 0
	v_readfirstlane_b32 s17, v174
	s_mov_b32 m0, s17
	s_nop 0
	global_load_lds_dwordx4 v[176:177], off
	v_subrev_u32_e32 v247, s0, v176
	v_lshl_add_u64 v[176:177], s[0:1], 0, v[180:181]
	v_add_u32_e32 v180, 0xa000, v179
	s_nop 0
	v_readfirstlane_b32 s17, v180
	v_add_u32_e32 v180, 0xc000, v179
	s_mov_b32 m0, s17
	v_readfirstlane_b32 s17, v180
	v_add_u32_e32 v180, 0xe000, v179
	global_load_lds_dwordx4 v[176:177], off
	v_subrev_u32_e32 v246, s0, v176
	v_lshl_add_u64 v[176:177], s[0:1], 0, v[184:185]
	s_mov_b32 m0, s17
	v_readfirstlane_b32 s17, v180
	global_load_lds_dwordx4 v[176:177], off
	v_subrev_u32_e32 v245, s0, v176
	v_lshl_add_u64 v[176:177], s[0:1], 0, v[182:183]
	s_mov_b32 m0, s17
	s_nop 0
	global_load_lds_dwordx4 v[176:177], off
	v_subrev_u32_e32 v244, s0, v176
	s_add_u32 s98, s6, 0x80
	s_addc_u32 s99, s7, 0
	s_add_u32 s100, s0, 0x80
	s_addc_u32 s101, s1, 0
	v_readfirstlane_b32 s26, v128
	s_nop 0
	s_nop 0
	v_add_u32_e32 v138, s16, v136
	v_add_u32_e32 v186, v138, v129
	v_add_u32_e32 v178, v138, v132
	ds_read_b128 v[138:141], v186
	ds_read_b128 v[158:161], v186 offset:2048
	ds_read_b128 v[142:145], v178 offset:32768
	ds_read_b128 v[146:149], v178 offset:34816
	ds_read_b128 v[150:153], v178 offset:36864
	ds_read_b128 v[154:157], v178 offset:38912
	ds_read_b128 v[162:165], v186 offset:4096
	ds_read_b128 v[166:169], v186 offset:6144
	ds_read_b128 v[170:173], v186 offset:8192
	s_branch .Lg_rot314_main

; DI float bflo(unsigned v) { return __uint_as_float(v << 16); }
; DI float bfhi(unsigned v) { return __uint_as_float(v & 0xffff0000u); }
;     ...
;     u16* dp = actD + (size_t)(b * SEQ + t0 + fr) * 512 + h * 128 + fq * 4;
; #pragma unroll
;     for (int dvs = 0; dvs < 8; ++dvs) {
;       u32x2 gz = *(const u32x2*)(dp + dvs * 16);
;       u32x2 ov = {pack2(o[dvs][0] * bflo(gz[0]), o[dvs][1] * bfhi(gz[0])),
;                   pack2(o[dvs][2] * bflo(gz[1]), o[dvs][3] * bfhi(gz[1]))};
;       if (!dry) *(u32x2*)(dp + dvs * 16) = ov;
;     }
;     __syncthreads();
.LBB0_367:
	s_or_b64 exec, exec, s[66:67]
	v_lshlrev_b64 v[28:29], 10, v[72:73]
	v_lshl_add_u64 v[28:29], s[4:5], 0, v[28:29]
	s_lshl_b32 s74, s58, 1
	v_lshl_add_u64 v[28:29], v[28:29], 0, s[74:75]
	v_mov_b32_e32 v71, v133
	v_lshl_add_u64 v[28:29], v[28:29], 0, v[70:71]
	global_load_dwordx2 v[86:87], v[28:29], off
	global_load_dwordx2 v[88:89], v[28:29], off offset:32
	global_load_dwordx2 v[90:91], v[28:29], off offset:64
	global_load_dwordx2 v[92:93], v[28:29], off offset:96
	global_load_dwordx2 v[94:95], v[28:29], off offset:128
	global_load_dwordx2 v[96:97], v[28:29], off offset:160
	global_load_dwordx2 v[98:99], v[28:29], off offset:192
	global_load_dwordx2 v[100:101], v[28:29], off offset:224
	v_mbcnt_lo_u32_b32 v40, -1, 0
	v_mbcnt_hi_u32_b32 v40, -1, v40
	v_bfe_u32 v40, v40, 4, 1
	v_mul_u32_u24_e32 v40, 24, v40
	v_mov_b32_e32 v41, 0
	v_lshl_add_u64 v[40:41], v[28:29], 0, v[40:41]
	s_add_i32 s57, s57, s72
	s_cmpk_lt_i32 s57, 0x400
	s_waitcnt vmcnt(7) lgkmcnt(0)
	v_lshlrev_b32_e32 v32, 16, v86
	v_and_b32_e32 v33, 0xffff0000, v86
	v_pk_mul_f32 v[32:33], v[44:45], v[32:33]
	s_nop 0
	v_cvt_pk_bf16_f32 v36, v32, v33
	v_lshlrev_b32_e32 v32, 16, v87
	v_and_b32_e32 v33, 0xffff0000, v87
	v_pk_mul_f32 v[32:33], v[46:47], v[32:33]
	s_nop 0
	v_cvt_pk_bf16_f32 v37, v32, v33
	s_waitcnt vmcnt(6) lgkmcnt(0)
	v_lshlrev_b32_e32 v32, 16, v88
	v_and_b32_e32 v33, 0xffff0000, v88
	v_lshlrev_b32_e32 v30, 16, v89
	v_and_b32_e32 v31, 0xffff0000, v89
	v_pk_mul_f32 v[24:25], v[24:25], v[32:33]
	v_pk_mul_f32 v[26:27], v[26:27], v[30:31]
	v_cvt_pk_bf16_f32 v38, v24, v25
	v_cvt_pk_bf16_f32 v39, v26, v27
	s_nop 1
	v_permlane16_swap_b32_e32 v36, v38
	v_permlane16_swap_b32_e32 v37, v39
	global_store_dwordx4 v[40:41], v[36:39], off
	s_waitcnt vmcnt(6) lgkmcnt(0)
	v_lshlrev_b32_e32 v26, 16, v90
	v_and_b32_e32 v27, 0xffff0000, v90
	v_lshlrev_b32_e32 v24, 16, v91
	v_and_b32_e32 v25, 0xffff0000, v91
	v_pk_mul_f32 v[20:21], v[20:21], v[26:27]
	v_pk_mul_f32 v[22:23], v[22:23], v[24:25]
	v_cvt_pk_bf16_f32 v36, v20, v21
	v_cvt_pk_bf16_f32 v37, v22, v23
	s_waitcnt vmcnt(5) lgkmcnt(0)
	v_lshlrev_b32_e32 v22, 16, v92
	v_and_b32_e32 v23, 0xffff0000, v92
	v_lshlrev_b32_e32 v20, 16, v93
	v_and_b32_e32 v21, 0xffff0000, v93
	v_pk_mul_f32 v[16:17], v[16:17], v[22:23]
	v_pk_mul_f32 v[18:19], v[18:19], v[20:21]
	v_cvt_pk_bf16_f32 v38, v16, v17
	v_cvt_pk_bf16_f32 v39, v18, v19
	s_nop 1
	v_permlane16_swap_b32_e32 v36, v38
	v_permlane16_swap_b32_e32 v37, v39
	global_store_dwordx4 v[40:41], v[36:39], off offset:64
	s_waitcnt vmcnt(5) lgkmcnt(0)
	v_lshlrev_b32_e32 v18, 16, v94
	v_and_b32_e32 v19, 0xffff0000, v94
	v_lshlrev_b32_e32 v16, 16, v95
	v_and_b32_e32 v17, 0xffff0000, v95
	v_pk_mul_f32 v[12:13], v[12:13], v[18:19]
	v_pk_mul_f32 v[14:15], v[14:15], v[16:17]
	v_cvt_pk_bf16_f32 v36, v12, v13
	v_cvt_pk_bf16_f32 v37, v14, v15
	s_waitcnt vmcnt(4) lgkmcnt(0)
	v_lshlrev_b32_e32 v14, 16, v96
	v_and_b32_e32 v15, 0xffff0000, v96
	v_lshlrev_b32_e32 v12, 16, v97
	v_and_b32_e32 v13, 0xffff0000, v97
	v_pk_mul_f32 v[8:9], v[8:9], v[14:15]
	v_pk_mul_f32 v[10:11], v[10:11], v[12:13]
	v_cvt_pk_bf16_f32 v38, v8, v9
	v_cvt_pk_bf16_f32 v39, v10, v11
	s_nop 1
	v_permlane16_swap_b32_e32 v36, v38
	v_permlane16_swap_b32_e32 v37, v39
	global_store_dwordx4 v[40:41], v[36:39], off offset:128
	s_waitcnt vmcnt(4) lgkmcnt(0)
	v_lshlrev_b32_e32 v10, 16, v98
	v_and_b32_e32 v11, 0xffff0000, v98
	v_lshlrev_b32_e32 v8, 16, v99
	v_and_b32_e32 v9, 0xffff0000, v99
	v_pk_mul_f32 v[4:5], v[4:5], v[10:11]
	v_pk_mul_f32 v[6:7], v[6:7], v[8:9]
	v_cvt_pk_bf16_f32 v36, v4, v5
	v_cvt_pk_bf16_f32 v37, v6, v7
	s_waitcnt vmcnt(3) lgkmcnt(0)
	v_lshlrev_b32_e32 v6, 16, v100
	v_and_b32_e32 v7, 0xffff0000, v100
	v_lshlrev_b32_e32 v4, 16, v101
	v_and_b32_e32 v5, 0xffff0000, v101
	v_pk_mul_f32 v[0:1], v[0:1], v[6:7]
	v_pk_mul_f32 v[2:3], v[2:3], v[4:5]
	v_cvt_pk_bf16_f32 v38, v0, v1
	v_cvt_pk_bf16_f32 v39, v2, v3
	s_nop 1
	v_permlane16_swap_b32_e32 v36, v38
	v_permlane16_swap_b32_e32 v37, v39
	global_store_dwordx4 v[40:41], v[36:39], off offset:192
	s_waitcnt lgkmcnt(0)
	s_barrier
	s_cbranch_scc0 .LBB0_403

; #define LDB_(dst, ks) _Pragma("unroll") for (int n = 0; n < 4; ++n) dst[n] = *(const bf16x8*)(sB + b_off + n * 2048 + (ks) * 1024)
; #define LDA_(dst, ks, h) _Pragma("unroll") for (int m = 0; m < 4; ++m) dst[m] = *(const bf16x8*)(sA + a_off + ((h) * 4 + m) * 2048 + (ks) * 1024)
; #define MMA_(A, B, h) _Pragma("unroll") for (int m = 0; m < 4; ++m) _Pragma("unroll") for (int n = 0; n < 4; ++n) \
;       acc[(h) * 4 + m][n] = SWAP ? MFMA16(B[n], A[m], acc[(h) * 4 + m][n]) : MFMA16(A[m], B[n], acc[(h) * 4 + m][n])
; template <int MF, int NF, bool SWAP = true>
; DI void gemm_main(f32x4 (&acc)[MF][NF], const u16* __restrict__ Ab, int lda, const u16* __restrict__ Bb, int ldb,
;                   int K, char* shm) {
;     ...
;   for (int t = 0; t < nt; ++t) {
;     const int cur = RING3 ? cur3 : (t & 1);
;     if constexpr (RING3) {
;       if (t + 2 < nt) G_STAGE(nxt3, t + 2);
;     } else {
;       if (t + 1 < nt) G_STAGE(cur ^ 1, t + 1);
;     }
;     const char* sA = shm + cur * STAGE;
;     const char* sB = sA + TILE_A;
;     if constexpr (MF == 8 && NF == 4) {
;       bf16x8 B0[4], B1[4], A0[4], A1[4], A2[4], A3[4];
;     ...
;       LDB_(B0, 0); LDA_(A0, 0, 0);
;       LDA_(A1, 0, 1); MMA_(A0, B0, 0);
;       LDB_(B1, 1); LDA_(A2, 1, 0); MMA_(A1, B0, 1);
;       LDA_(A3, 1, 1); MMA_(A2, B1, 0);
;       MMA_(A3, B1, 1);
.LBB0_553:
	s_and_b32 s21, s18, 0x10000
	s_cmp_gt_u32 s20, 2
	s_cbranch_scc1 .Lg_rot553_last
	s_cmp_eq_u32 s20, 0
	s_cbranch_scc1 .Lg_rot553_first
	v_mfma_f32_16x16x32_bf16 v[60:63], v[196:199], v[212:215], v[60:63]
	s_xor_b32 s22, s21, 0x10000
	v_mfma_f32_16x16x32_bf16 v[56:59], v[216:219], v[212:215], v[56:59]
	s_add_u32 s22, s22, s26
	s_add_u32 m0, s22, 0x0
	v_mfma_f32_16x16x32_bf16 v[52:55], v[220:223], v[212:215], v[52:55]
	global_load_lds_dwordx4 v251, s[98:99]
	s_add_u32 m0, s22, 0x2000
	v_mfma_f32_16x16x32_bf16 v[48:51], v[224:227], v[212:215], v[48:51]
	global_load_lds_dwordx4 v250, s[98:99]
	s_add_u32 m0, s22, 0x4000
	v_mfma_f32_16x16x32_bf16 v[44:47], v[196:199], v[228:231], v[44:47]
	global_load_lds_dwordx4 v249, s[98:99]
	s_add_u32 m0, s22, 0x6000
	v_mfma_f32_16x16x32_bf16 v[40:43], v[216:219], v[228:231], v[40:43]
	global_load_lds_dwordx4 v248, s[98:99]
	s_add_u32 m0, s22, 0x8000
	v_mfma_f32_16x16x32_bf16 v[36:39], v[220:223], v[228:231], v[36:39]
	global_load_lds_dwordx4 v247, s[100:101]
	s_add_u32 m0, s22, 0xa000
	v_mfma_f32_16x16x32_bf16 v[32:35], v[224:227], v[228:231], v[32:35]
	global_load_lds_dwordx4 v246, s[100:101]
	s_add_u32 m0, s22, 0xc000
	v_mfma_f32_16x16x32_bf16 v[28:31], v[196:199], v[232:235], v[28:31]
	global_load_lds_dwordx4 v245, s[100:101]
	s_add_u32 m0, s22, 0xe000
	v_mfma_f32_16x16x32_bf16 v[24:27], v[216:219], v[232:235], v[24:27]
	global_load_lds_dwordx4 v244, s[100:101]
	v_mfma_f32_16x16x32_bf16 v[20:23], v[220:223], v[232:235], v[20:23]
	s_add_u32 s98, s98, 0x80
	s_addc_u32 s99, s99, 0
	s_add_u32 s100, s100, 0x80
	s_addc_u32 s101, s101, 0
	v_add_u32_e32 v162, s21, v143
	v_add_u32_e32 v186, v162, v142
	ds_read_b128 v[146:149], v186 offset:32768
	ds_read_b128 v[150:153], v186 offset:34816
	ds_read_b128 v[154:157], v186 offset:36864
	ds_read_b128 v[158:161], v186 offset:38912
	v_add_u32_e32 v194, v162, v141
	ds_read_b128 v[162:165], v194
	ds_read_b128 v[166:169], v194 offset:2048
	ds_read_b128 v[170:173], v194 offset:4096
	ds_read_b128 v[174:177], v194 offset:6144
	ds_read_b128 v[178:181], v194 offset:8192
	v_mfma_f32_16x16x32_bf16 v[16:19], v[224:227], v[232:235], v[16:19]
	v_mfma_f32_16x16x32_bf16 v[12:15], v[196:199], v[236:239], v[12:15]
	v_mfma_f32_16x16x32_bf16 v[4:7], v[216:219], v[236:239], v[4:7]
	v_mfma_f32_16x16x32_bf16 v[0:3], v[220:223], v[236:239], v[0:3]
	v_mfma_f32_16x16x32_bf16 v[8:11], v[224:227], v[236:239], v[8:11]
	s_branch .Lg_rot553_main
.Lg_rot553_first:
	s_xor_b32 s22, s21, 0x10000
	v_add_u32_e32 v187, s19, v145
	v_add_u32_e32 v195, s22, v132
	v_add_u32_e32 v182, 64, v187
	v_ashrrev_i32_e32 v183, 31, v182
	v_readfirstlane_b32 s22, v195
	v_lshl_add_u64 v[182:183], v[182:183], 1, s[4:5]
	s_mov_b32 m0, s22
	v_add_u32_e32 v211, 0x2000, v195
	global_load_lds_dwordx4 v[182:183], off
	v_subrev_u32_e32 v251, s4, v182
	v_add_u32_e32 v182, 0x7040, v187
	v_ashrrev_i32_e32 v183, 31, v182
	v_readfirstlane_b32 s22, v211
	v_lshl_add_u64 v[182:183], v[182:183], 1, s[4:5]
	s_mov_b32 m0, s22
	v_add_u32_e32 v211, 0x4000, v195
	global_load_lds_dwordx4 v[182:183], off
	v_subrev_u32_e32 v250, s4, v182
	v_add_u32_e32 v182, 0xe040, v187
	v_ashrrev_i32_e32 v183, 31, v182
	v_readfirstlane_b32 s22, v211
	v_lshl_add_u64 v[182:183], v[182:183], 1, s[4:5]
	s_mov_b32 m0, s22
	v_add_u32_e32 v211, s19, v144
	global_load_lds_dwordx4 v[182:183], off
	v_subrev_u32_e32 v249, s4, v182
	v_add_u32_e32 v182, 0x15040, v187
	v_add_u32_e32 v187, 0x6000, v195
	v_ashrrev_i32_e32 v183, 31, v182
	v_readfirstlane_b32 s22, v187
	v_lshl_add_u64 v[182:183], v[182:183], 1, s[4:5]
	s_mov_b32 m0, s22
	v_add_u32_e32 v187, 0x8000, v195
	global_load_lds_dwordx4 v[182:183], off
	v_subrev_u32_e32 v248, s4, v182
	v_add_u32_e32 v182, 64, v211
	v_ashrrev_i32_e32 v183, 31, v182
	v_readfirstlane_b32 s22, v187
	v_lshl_add_u64 v[182:183], v[182:183], 1, s[6:7]
	s_mov_b32 m0, s22
	v_add_u32_e32 v187, 0xa000, v195
	global_load_lds_dwordx4 v[182:183], off
	v_subrev_u32_e32 v247, s6, v182
	v_add_u32_e32 v182, 0x4040, v211
	v_ashrrev_i32_e32 v183, 31, v182
	v_readfirstlane_b32 s22, v187
	v_lshl_add_u64 v[182:183], v[182:183], 1, s[6:7]
	s_mov_b32 m0, s22
	v_add_u32_e32 v187, 0xc000, v195
	global_load_lds_dwordx4 v[182:183], off
	v_subrev_u32_e32 v246, s6, v182
	v_add_u32_e32 v182, 0x8040, v211
	v_ashrrev_i32_e32 v183, 31, v182
	v_readfirstlane_b32 s22, v187
	v_lshl_add_u64 v[182:183], v[182:183], 1, s[6:7]
	s_mov_b32 m0, s22
	v_add_u32_e32 v195, 0xe000, v195
	global_load_lds_dwordx4 v[182:183], off
	v_subrev_u32_e32 v245, s6, v182
	v_add_u32_e32 v182, 0xc040, v211
	v_ashrrev_i32_e32 v183, 31, v182
	v_readfirstlane_b32 s22, v195
	v_lshl_add_u64 v[182:183], v[182:183], 1, s[6:7]
	s_mov_b32 m0, s22
	s_nop 0
	global_load_lds_dwordx4 v[182:183], off
	v_subrev_u32_e32 v244, s6, v182
	s_add_u32 s98, s4, 0x80
	s_addc_u32 s99, s5, 0
	s_add_u32 s100, s6, 0x80
	s_addc_u32 s101, s7, 0
	v_readfirstlane_b32 s26, v132
	s_nop 0
	s_nop 0
	v_add_u32_e32 v162, s21, v143
	v_add_u32_e32 v186, v162, v142
	ds_read_b128 v[146:149], v186 offset:32768
	ds_read_b128 v[150:153], v186 offset:34816
	ds_read_b128 v[154:157], v186 offset:36864
	ds_read_b128 v[158:161], v186 offset:38912
	v_add_u32_e32 v194, v162, v141
	ds_read_b128 v[162:165], v194
	ds_read_b128 v[166:169], v194 offset:2048
	ds_read_b128 v[170:173], v194 offset:4096
	ds_read_b128 v[174:177], v194 offset:6144
	ds_read_b128 v[178:181], v194 offset:8192
	s_branch .Lg_rot553_main

; #define LDB_(dst, ks) _Pragma("unroll") for (int n = 0; n < 4; ++n) dst[n] = *(const bf16x8*)(sB + b_off + n * 2048 + (ks) * 1024)
; #define LDA_(dst, ks, h) _Pragma("unroll") for (int m = 0; m < 4; ++m) dst[m] = *(const bf16x8*)(sA + a_off + ((h) * 4 + m) * 2048 + (ks) * 1024)
; #define MMA_(A, B, h) _Pragma("unroll") for (int m = 0; m < 4; ++m) _Pragma("unroll") for (int n = 0; n < 4; ++n) \
;       acc[(h) * 4 + m][n] = SWAP ? MFMA16(B[n], A[m], acc[(h) * 4 + m][n]) : MFMA16(A[m], B[n], acc[(h) * 4 + m][n])
; template <int MF, int NF, bool SWAP = true>
; DI void gemm_main(f32x4 (&acc)[MF][NF], const u16* __restrict__ Ab, int lda, const u16* __restrict__ Bb, int ldb,
;                   int K, char* shm) {
;     ...
;   for (int t = 0; t < nt; ++t) {
;     const int cur = RING3 ? cur3 : (t & 1);
;     if constexpr (RING3) {
;       if (t + 2 < nt) G_STAGE(nxt3, t + 2);
;     } else {
;       if (t + 1 < nt) G_STAGE(cur ^ 1, t + 1);
;     }
;     const char* sA = shm + cur * STAGE;
;     const char* sB = sA + TILE_A;
;     if constexpr (MF == 8 && NF == 4) {
;       bf16x8 B0[4], B1[4], A0[4], A1[4], A2[4], A3[4];
;     ...
;       LDB_(B0, 0); LDA_(A0, 0, 0);
;       LDA_(A1, 0, 1); MMA_(A0, B0, 0);
;       LDB_(B1, 1); LDA_(A2, 1, 0); MMA_(A1, B0, 1);
;       LDA_(A3, 1, 1); MMA_(A2, B1, 0);
;       MMA_(A3, B1, 1);
.LBB0_589:
	s_and_b32 s21, s16, 0x10000
	s_cmp_gt_u32 s15, 14
	s_cbranch_scc1 .Lg_rot589_last
	s_cmp_eq_u32 s15, 0
	s_cbranch_scc1 .Lg_rot589_first
	v_mfma_f32_16x16x32_bf16 v[60:63], v[186:189], v[190:193], v[60:63]
	s_xor_b32 s22, s21, 0x10000
	v_mfma_f32_16x16x32_bf16 v[56:59], v[194:197], v[190:193], v[56:59]
	s_add_u32 s22, s22, s26
	s_add_u32 m0, s22, 0x0
	v_mfma_f32_16x16x32_bf16 v[52:55], v[198:201], v[190:193], v[52:55]
	global_load_lds_dwordx4 v251, s[98:99]
	s_add_u32 m0, s22, 0x2000
	v_mfma_f32_16x16x32_bf16 v[48:51], v[218:221], v[190:193], v[48:51]
	global_load_lds_dwordx4 v250, s[98:99]
	s_add_u32 m0, s22, 0x4000
	v_mfma_f32_16x16x32_bf16 v[44:47], v[186:189], v[222:225], v[44:47]
	global_load_lds_dwordx4 v249, s[98:99]
	s_add_u32 m0, s22, 0x6000
	v_mfma_f32_16x16x32_bf16 v[40:43], v[194:197], v[222:225], v[40:43]
	global_load_lds_dwordx4 v248, s[98:99]
	s_add_u32 m0, s22, 0x8000
	v_mfma_f32_16x16x32_bf16 v[36:39], v[198:201], v[222:225], v[36:39]
	global_load_lds_dwordx4 v247, s[100:101]
	s_add_u32 m0, s22, 0xa000
	v_mfma_f32_16x16x32_bf16 v[32:35], v[218:221], v[222:225], v[32:35]
	global_load_lds_dwordx4 v246, s[100:101]
	s_add_u32 m0, s22, 0xc000
	v_mfma_f32_16x16x32_bf16 v[28:31], v[186:189], v[226:229], v[28:31]
	global_load_lds_dwordx4 v245, s[100:101]
	s_add_u32 m0, s22, 0xe000
	v_mfma_f32_16x16x32_bf16 v[24:27], v[194:197], v[226:229], v[24:27]
	global_load_lds_dwordx4 v244, s[100:101]
	v_mfma_f32_16x16x32_bf16 v[20:23], v[198:201], v[226:229], v[20:23]
	s_add_u32 s98, s98, 0x80
	s_addc_u32 s99, s99, 0
	s_add_u32 s100, s100, 0x80
	s_addc_u32 s101, s101, 0
	v_add_u32_e32 v137, s21, v132
	v_add_u32_e32 v178, v137, v131
	ds_read_b128 v[138:141], v178 offset:32768
	ds_read_b128 v[142:145], v178 offset:34816
	ds_read_b128 v[146:149], v178 offset:36864
	ds_read_b128 v[150:153], v178 offset:38912
	v_add_u32_e32 v137, v137, v129
	ds_read_b128 v[154:157], v137
	ds_read_b128 v[158:161], v137 offset:2048
	ds_read_b128 v[162:165], v137 offset:4096
	ds_read_b128 v[166:169], v137 offset:6144
	ds_read_b128 v[170:173], v137 offset:8192
	v_mfma_f32_16x16x32_bf16 v[16:19], v[218:221], v[226:229], v[16:19]
	v_mfma_f32_16x16x32_bf16 v[12:15], v[186:189], v[230:233], v[12:15]
	v_mfma_f32_16x16x32_bf16 v[8:11], v[194:197], v[230:233], v[8:11]
	v_mfma_f32_16x16x32_bf16 v[4:7], v[198:201], v[230:233], v[4:7]
	v_mfma_f32_16x16x32_bf16 v[0:3], v[218:221], v[230:233], v[0:3]
	s_branch .Lg_rot589_main
.Lg_rot589_first:
	v_add_u32_e32 v174, s13, v136
	s_xor_b32 s22, s21, 0x10000
	v_add_u32_e32 v176, 64, v174
	v_add_u32_e32 v179, s22, v128
	v_ashrrev_i32_e32 v177, 31, v176
	v_lshlrev_b64 v[176:177], 1, v[176:177]
	v_readfirstlane_b32 s22, v179
	v_lshl_add_u64 v[180:181], s[0:1], 0, v[176:177]
	s_mov_b32 m0, s22
	v_add_u32_e32 v182, 0x2000, v179
	global_load_lds_dwordx4 v[180:181], off
	v_subrev_u32_e32 v251, s0, v180
	v_add_u32_e32 v180, 0x10040, v174
	v_ashrrev_i32_e32 v181, 31, v180
	v_lshlrev_b64 v[180:181], 1, v[180:181]
	v_readfirstlane_b32 s22, v182
	v_lshl_add_u64 v[184:185], s[0:1], 0, v[180:181]
	s_mov_b32 m0, s22
	v_add_u32_e32 v175, 0x4000, v179
	global_load_lds_dwordx4 v[184:185], off
	v_subrev_u32_e32 v250, s0, v184
	v_add_u32_e32 v184, 0x20040, v174
	v_ashrrev_i32_e32 v185, 31, v184
	v_lshlrev_b64 v[184:185], 1, v[184:185]
	v_readfirstlane_b32 s22, v175
	v_lshl_add_u64 v[182:183], s[0:1], 0, v[184:185]
	s_mov_b32 m0, s22
	v_add_u32_e32 v217, 0x6000, v179
	global_load_lds_dwordx4 v[182:183], off
	v_subrev_u32_e32 v249, s0, v182
	v_add_u32_e32 v182, 0x30040, v174
	v_ashrrev_i32_e32 v183, 31, v182
	v_lshlrev_b64 v[182:183], 1, v[182:183]
	v_readfirstlane_b32 s22, v217
	v_lshl_add_u64 v[174:175], s[0:1], 0, v[182:183]
	s_mov_b32 m0, s22
	v_lshl_add_u64 v[176:177], s[4:5], 0, v[176:177]
	global_load_lds_dwordx4 v[174:175], off
	v_subrev_u32_e32 v248, s0, v174
	v_add_u32_e32 v174, 0x8000, v179
	s_nop 0
	v_readfirstlane_b32 s22, v174
	s_mov_b32 m0, s22
	s_nop 0
	global_load_lds_dwordx4 v[176:177], off
	v_subrev_u32_e32 v247, s4, v176
	v_lshl_add_u64 v[176:177], s[4:5], 0, v[180:181]
	v_add_u32_e32 v180, 0xa000, v179
	s_nop 0
	v_readfirstlane_b32 s22, v180
	v_add_u32_e32 v180, 0xc000, v179
	s_mov_b32 m0, s22
	v_readfirstlane_b32 s22, v180
	v_add_u32_e32 v179, 0xe000, v179
	global_load_lds_dwordx4 v[176:177], off
	v_subrev_u32_e32 v246, s4, v176
	v_lshl_add_u64 v[176:177], s[4:5], 0, v[184:185]
	s_mov_b32 m0, s22
	v_readfirstlane_b32 s22, v179
	global_load_lds_dwordx4 v[176:177], off
	v_subrev_u32_e32 v245, s4, v176
	v_lshl_add_u64 v[176:177], s[4:5], 0, v[182:183]
	s_mov_b32 m0, s22
	s_nop 0
	global_load_lds_dwordx4 v[176:177], off
	v_subrev_u32_e32 v244, s4, v176
	s_add_u32 s98, s0, 0x80
	s_addc_u32 s99, s1, 0
	s_add_u32 s100, s4, 0x80
	s_addc_u32 s101, s5, 0
	v_readfirstlane_b32 s26, v128
	s_nop 0
	s_nop 0
	v_add_u32_e32 v137, s21, v132
	v_add_u32_e32 v178, v137, v131
	ds_read_b128 v[138:141], v178 offset:32768
	ds_read_b128 v[142:145], v178 offset:34816
	ds_read_b128 v[146:149], v178 offset:36864
	ds_read_b128 v[150:153], v178 offset:38912
	v_add_u32_e32 v137, v137, v129
	ds_read_b128 v[154:157], v137
	ds_read_b128 v[158:161], v137 offset:2048
	ds_read_b128 v[162:165], v137 offset:4096
	ds_read_b128 v[166:169], v137 offset:6144
	ds_read_b128 v[170:173], v137 offset:8192
	s_branch .Lg_rot589_main

; #define LDB_(dst, ks) _Pragma("unroll") for (int n = 0; n < 4; ++n) dst[n] = *(const bf16x8*)(sB + b_off + n * 2048 + (ks) * 1024)
; #define LDA_(dst, ks, h) _Pragma("unroll") for (int m = 0; m < 4; ++m) dst[m] = *(const bf16x8*)(sA + a_off + ((h) * 4 + m) * 2048 + (ks) * 1024)
; #define MMA_(A, B, h) _Pragma("unroll") for (int m = 0; m < 4; ++m) _Pragma("unroll") for (int n = 0; n < 4; ++n) \
;       acc[(h) * 4 + m][n] = SWAP ? MFMA16(B[n], A[m], acc[(h) * 4 + m][n]) : MFMA16(A[m], B[n], acc[(h) * 4 + m][n])
; template <int MF, int NF, bool SWAP = true>
; DI void gemm_main(f32x4 (&acc)[MF][NF], const u16* __restrict__ Ab, int lda, const u16* __restrict__ Bb, int ldb,
;                   int K, char* shm) {
;     ...
;   for (int t = 0; t < nt; ++t) {
;     const int cur = RING3 ? cur3 : (t & 1);
;     if constexpr (RING3) {
;       if (t + 2 < nt) G_STAGE(nxt3, t + 2);
;     } else {
;       if (t + 1 < nt) G_STAGE(cur ^ 1, t + 1);
;     }
;     const char* sA = shm + cur * STAGE;
;     const char* sB = sA + TILE_A;
;     if constexpr (MF == 8 && NF == 4) {
;       bf16x8 B0[4], B1[4], A0[4], A1[4], A2[4], A3[4];
;     ...
;       LDB_(B0, 0); LDA_(A0, 0, 0);
;       LDA_(A1, 0, 1); MMA_(A0, B0, 0);
;       LDB_(B1, 1); LDA_(A2, 1, 0); MMA_(A1, B0, 1);
;       LDA_(A3, 1, 1); MMA_(A2, B1, 0);
;       MMA_(A3, B1, 1);
.LBB0_819:
	s_and_b32 s19, s17, 0x10000
	s_cmp_gt_u32 s18, 2
	s_cbranch_scc1 .Lg_rot819_last
	s_cmp_eq_u32 s18, 0
	s_cbranch_scc1 .Lg_rot819_first
	v_mfma_f32_16x16x32_bf16 v[60:63], v[186:189], v[190:193], v[60:63]
	s_xor_b32 s20, s19, 0x10000
	v_mfma_f32_16x16x32_bf16 v[56:59], v[194:197], v[190:193], v[56:59]
	s_add_u32 s20, s20, s26
	s_add_u32 m0, s20, 0x0
	v_mfma_f32_16x16x32_bf16 v[52:55], v[198:201], v[190:193], v[52:55]
	global_load_lds_dwordx4 v251, s[98:99]
	s_add_u32 m0, s20, 0x2000
	v_mfma_f32_16x16x32_bf16 v[48:51], v[218:221], v[190:193], v[48:51]
	global_load_lds_dwordx4 v250, s[98:99]
	s_add_u32 m0, s20, 0x4000
	v_mfma_f32_16x16x32_bf16 v[44:47], v[186:189], v[222:225], v[44:47]
	global_load_lds_dwordx4 v249, s[98:99]
	s_add_u32 m0, s20, 0x6000
	v_mfma_f32_16x16x32_bf16 v[40:43], v[194:197], v[222:225], v[40:43]
	global_load_lds_dwordx4 v248, s[98:99]
	s_add_u32 m0, s20, 0x8000
	v_mfma_f32_16x16x32_bf16 v[36:39], v[198:201], v[222:225], v[36:39]
	global_load_lds_dwordx4 v247, s[100:101]
	s_add_u32 m0, s20, 0xa000
	v_mfma_f32_16x16x32_bf16 v[32:35], v[218:221], v[222:225], v[32:35]
	global_load_lds_dwordx4 v246, s[100:101]
	s_add_u32 m0, s20, 0xc000
	v_mfma_f32_16x16x32_bf16 v[28:31], v[186:189], v[226:229], v[28:31]
	global_load_lds_dwordx4 v245, s[100:101]
	s_add_u32 m0, s20, 0xe000
	v_mfma_f32_16x16x32_bf16 v[24:27], v[194:197], v[226:229], v[24:27]
	global_load_lds_dwordx4 v244, s[100:101]
	v_mfma_f32_16x16x32_bf16 v[20:23], v[198:201], v[226:229], v[20:23]
	s_add_u32 s98, s98, 0x80
	s_addc_u32 s99, s99, 0
	s_add_u32 s100, s100, 0x80
	s_addc_u32 s101, s101, 0
	v_add_u32_e32 v137, s19, v132
	v_add_u32_e32 v178, v137, v131
	ds_read_b128 v[138:141], v178 offset:32768
	ds_read_b128 v[142:145], v178 offset:34816
	ds_read_b128 v[146:149], v178 offset:36864
	ds_read_b128 v[150:153], v178 offset:38912
	v_add_u32_e32 v137, v137, v130
	ds_read_b128 v[154:157], v137
	ds_read_b128 v[158:161], v137 offset:2048
	ds_read_b128 v[162:165], v137 offset:4096
	ds_read_b128 v[166:169], v137 offset:6144
	ds_read_b128 v[170:173], v137 offset:8192
	v_mfma_f32_16x16x32_bf16 v[16:19], v[218:221], v[226:229], v[16:19]
	v_mfma_f32_16x16x32_bf16 v[8:11], v[186:189], v[230:233], v[8:11]
	v_mfma_f32_16x16x32_bf16 v[4:7], v[194:197], v[230:233], v[4:7]
	v_mfma_f32_16x16x32_bf16 v[0:3], v[198:201], v[230:233], v[0:3]
	v_mfma_f32_16x16x32_bf16 v[12:15], v[218:221], v[230:233], v[12:15]
	s_branch .Lg_rot819_main
.Lg_rot819_first:
	v_add_u32_e32 v174, s1, v136
	s_xor_b32 s20, s19, 0x10000
	v_add_u32_e32 v176, 64, v174
	v_add_u32_e32 v179, s20, v129
	v_ashrrev_i32_e32 v177, 31, v176
	v_lshlrev_b64 v[176:177], 1, v[176:177]
	v_readfirstlane_b32 s20, v179
	v_lshl_add_u64 v[180:181], s[6:7], 0, v[176:177]
	s_mov_b32 m0, s20
	v_add_u32_e32 v182, 0x2000, v179
	global_load_lds_dwordx4 v[180:181], off
	v_subrev_u32_e32 v251, s6, v180
	v_add_u32_e32 v180, 0x8040, v174
	v_ashrrev_i32_e32 v181, 31, v180
	v_lshlrev_b64 v[180:181], 1, v[180:181]
	v_readfirstlane_b32 s20, v182
	v_lshl_add_u64 v[184:185], s[6:7], 0, v[180:181]
	s_mov_b32 m0, s20
	v_add_u32_e32 v175, 0x4000, v179
	global_load_lds_dwordx4 v[184:185], off
	v_subrev_u32_e32 v250, s6, v184
	v_add_u32_e32 v184, 0x10040, v174
	v_ashrrev_i32_e32 v185, 31, v184
	v_lshlrev_b64 v[184:185], 1, v[184:185]
	v_readfirstlane_b32 s20, v175
	v_lshl_add_u64 v[182:183], s[6:7], 0, v[184:185]
	s_mov_b32 m0, s20
	v_add_u32_e32 v217, 0x6000, v179
	global_load_lds_dwordx4 v[182:183], off
	v_subrev_u32_e32 v249, s6, v182
	v_add_u32_e32 v182, 0x18040, v174
	v_ashrrev_i32_e32 v183, 31, v182
	v_lshlrev_b64 v[182:183], 1, v[182:183]
	v_readfirstlane_b32 s20, v217
	v_lshl_add_u64 v[174:175], s[6:7], 0, v[182:183]
	s_mov_b32 m0, s20
	v_lshl_add_u64 v[176:177], s[8:9], 0, v[176:177]
	global_load_lds_dwordx4 v[174:175], off
	v_subrev_u32_e32 v248, s6, v174
	v_add_u32_e32 v174, 0x8000, v179
	s_nop 0
	v_readfirstlane_b32 s20, v174
	s_mov_b32 m0, s20
	s_nop 0
	global_load_lds_dwordx4 v[176:177], off
	v_subrev_u32_e32 v247, s8, v176
	v_lshl_add_u64 v[176:177], s[8:9], 0, v[180:181]
	v_add_u32_e32 v180, 0xa000, v179
	s_nop 0
	v_readfirstlane_b32 s20, v180
	v_add_u32_e32 v180, 0xc000, v179
	s_mov_b32 m0, s20
	v_readfirstlane_b32 s20, v180
	v_add_u32_e32 v179, 0xe000, v179
	global_load_lds_dwordx4 v[176:177], off
	v_subrev_u32_e32 v246, s8, v176
	v_lshl_add_u64 v[176:177], s[8:9], 0, v[184:185]
	s_mov_b32 m0, s20
	v_readfirstlane_b32 s20, v179
	global_load_lds_dwordx4 v[176:177], off
	v_subrev_u32_e32 v245, s8, v176
	v_lshl_add_u64 v[176:177], s[8:9], 0, v[182:183]
	s_mov_b32 m0, s20
	s_nop 0
	global_load_lds_dwordx4 v[176:177], off
	v_subrev_u32_e32 v244, s8, v176
	s_add_u32 s98, s6, 0x80
	s_addc_u32 s99, s7, 0
	s_add_u32 s100, s8, 0x80
	s_addc_u32 s101, s9, 0
	v_readfirstlane_b32 s26, v129
	s_nop 0
	s_nop 0
	v_add_u32_e32 v137, s19, v132
	v_add_u32_e32 v178, v137, v131
	ds_read_b128 v[138:141], v178 offset:32768
	ds_read_b128 v[142:145], v178 offset:34816
	ds_read_b128 v[146:149], v178 offset:36864
	ds_read_b128 v[150:153], v178 offset:38912
	v_add_u32_e32 v137, v137, v130
	ds_read_b128 v[154:157], v137
	ds_read_b128 v[158:161], v137 offset:2048
	ds_read_b128 v[162:165], v137 offset:4096
	ds_read_b128 v[166:169], v137 offset:6144
	ds_read_b128 v[170:173], v137 offset:8192
	s_branch .Lg_rot819_main

; #define LDB_(dst, ks) _Pragma("unroll") for (int n = 0; n < 4; ++n) dst[n] = *(const bf16x8*)(sB + b_off + n * 2048 + (ks) * 1024)
; #define LDA_(dst, ks, h) _Pragma("unroll") for (int m = 0; m < 4; ++m) dst[m] = *(const bf16x8*)(sA + a_off + ((h) * 4 + m) * 2048 + (ks) * 1024)
; #define MMA_(A, B, h) _Pragma("unroll") for (int m = 0; m < 4; ++m) _Pragma("unroll") for (int n = 0; n < 4; ++n) \
;       acc[(h) * 4 + m][n] = SWAP ? MFMA16(B[n], A[m], acc[(h) * 4 + m][n]) : MFMA16(A[m], B[n], acc[(h) * 4 + m][n])
; template <int MF, int NF, bool SWAP = true>
; DI void gemm_main(f32x4 (&acc)[MF][NF], const u16* __restrict__ Ab, int lda, const u16* __restrict__ Bb, int ldb,
;                   int K, char* shm) {
;     ...
;   for (int t = 0; t < nt; ++t) {
;     const int cur = RING3 ? cur3 : (t & 1);
;     if constexpr (RING3) {
;       if (t + 2 < nt) G_STAGE(nxt3, t + 2);
;     } else {
;       if (t + 1 < nt) G_STAGE(cur ^ 1, t + 1);
;     }
;     const char* sA = shm + cur * STAGE;
;     const char* sB = sA + TILE_A;
;     if constexpr (MF == 8 && NF == 4) {
;       bf16x8 B0[4], B1[4], A0[4], A1[4], A2[4], A3[4];
;     ...
;       LDB_(B0, 0); LDA_(A0, 0, 0);
;       LDA_(A1, 0, 1); MMA_(A0, B0, 0);
;       LDB_(B1, 1); LDA_(A2, 1, 0); MMA_(A1, B0, 1);
;       LDA_(A3, 1, 1); MMA_(A2, B1, 0);
;       MMA_(A3, B1, 1);
.LBB0_874:
	s_and_b32 s23, s21, 0x10000
	s_cmp_gt_u32 s22, 14
	s_cbranch_scc1 .Lg_rot874_last
	s_cmp_eq_u32 s22, 0
	s_cbranch_scc1 .Lg_rot874_first
	v_mfma_f32_16x16x32_bf16 v[60:63], v[218:221], v[222:225], v[60:63]
	s_xor_b32 s24, s23, 0x10000
	v_mfma_f32_16x16x32_bf16 v[56:59], v[226:229], v[222:225], v[56:59]
	s_add_u32 s24, s24, s26
	s_add_u32 m0, s24, 0x0
	v_mfma_f32_16x16x32_bf16 v[52:55], v[230:233], v[222:225], v[52:55]
	global_load_lds_dwordx4 v255, s[98:99]
	s_add_u32 m0, s24, 0x2000
	v_mfma_f32_16x16x32_bf16 v[48:51], v[234:237], v[222:225], v[48:51]
	global_load_lds_dwordx4 v254, s[98:99]
	s_add_u32 m0, s24, 0x4000
	v_mfma_f32_16x16x32_bf16 v[44:47], v[218:221], v[238:241], v[44:47]
	global_load_lds_dwordx4 v251, s[98:99]
	s_add_u32 m0, s24, 0x6000
	v_mfma_f32_16x16x32_bf16 v[40:43], v[226:229], v[238:241], v[40:43]
	global_load_lds_dwordx4 v250, s[98:99]
	s_add_u32 m0, s24, 0x8000
	v_mfma_f32_16x16x32_bf16 v[36:39], v[230:233], v[238:241], v[36:39]
	global_load_lds_dwordx4 v255, s[100:101]
	s_add_u32 m0, s24, 0xa000
	v_mfma_f32_16x16x32_bf16 v[32:35], v[234:237], v[238:241], v[32:35]
	global_load_lds_dwordx4 v254, s[100:101]
	s_add_u32 m0, s24, 0xc000
	v_mfma_f32_16x16x32_bf16 v[28:31], v[218:221], v[242:245], v[28:31]
	global_load_lds_dwordx4 v251, s[100:101]
	s_add_u32 m0, s24, 0xe000
	v_mfma_f32_16x16x32_bf16 v[24:27], v[226:229], v[242:245], v[24:27]
	global_load_lds_dwordx4 v250, s[100:101]
	v_mfma_f32_16x16x32_bf16 v[16:19], v[230:233], v[242:245], v[16:19]
	s_add_u32 s98, s98, 0x80
	s_addc_u32 s99, s99, 0
	s_add_u32 s100, s100, 0x80
	s_addc_u32 s101, s101, 0
	v_add_u32_e32 v153, s23, v151
	v_add_u32_e32 v194, v153, v150
	ds_read_b128 v[154:157], v194 offset:32768
	ds_read_b128 v[158:161], v194 offset:34816
	ds_read_b128 v[162:165], v194 offset:36864
	ds_read_b128 v[166:169], v194 offset:38912
	v_add_u32_e32 v153, v153, v149
	ds_read_b128 v[170:173], v153
	ds_read_b128 v[174:177], v153 offset:2048
	ds_read_b128 v[178:181], v153 offset:4096
	ds_read_b128 v[182:185], v153 offset:6144
	ds_read_b128 v[186:189], v153 offset:8192
	v_mfma_f32_16x16x32_bf16 v[12:15], v[234:237], v[242:245], v[12:15]
	v_mfma_f32_16x16x32_bf16 v[8:11], v[218:221], v[246:249], v[8:11]
	v_mfma_f32_16x16x32_bf16 v[4:7], v[226:229], v[246:249], v[4:7]
	v_mfma_f32_16x16x32_bf16 v[0:3], v[230:233], v[246:249], v[0:3]
	v_mfma_f32_16x16x32_bf16 v[20:23], v[234:237], v[246:249], v[20:23]
	s_branch .Lg_rot874_main
.Lg_rot874_first:
	v_add_u32_e32 v190, s11, v152
	s_xor_b32 s24, s23, 0x10000
	v_add_u32_e32 v192, 64, v190
	v_add_u32_e32 v195, s24, v148
	v_ashrrev_i32_e32 v193, 31, v192
	v_lshlrev_b64 v[192:193], 1, v[192:193]
	v_readfirstlane_b32 s24, v195
	v_lshl_add_u64 v[196:197], s[12:13], 0, v[192:193]
	s_mov_b32 m0, s24
	v_add_u32_e32 v198, 0x2000, v195
	global_load_lds_dwordx4 v[196:197], off
	v_subrev_u32_e32 v255, s12, v196
	v_add_u32_e32 v196, 0x10040, v190
	v_ashrrev_i32_e32 v197, 31, v196
	v_lshlrev_b64 v[196:197], 1, v[196:197]
	v_readfirstlane_b32 s24, v198
	v_lshl_add_u64 v[200:201], s[12:13], 0, v[196:197]
	s_mov_b32 m0, s24
	v_add_u32_e32 v191, 0x4000, v195
	global_load_lds_dwordx4 v[200:201], off
	v_subrev_u32_e32 v254, s12, v200
	v_add_u32_e32 v200, 0x20040, v190
	v_ashrrev_i32_e32 v201, 31, v200
	v_lshlrev_b64 v[200:201], 1, v[200:201]
	v_readfirstlane_b32 s24, v191
	v_lshl_add_u64 v[198:199], s[12:13], 0, v[200:201]
	s_mov_b32 m0, s24
	v_add_u32_e32 v217, 0x6000, v195
	global_load_lds_dwordx4 v[198:199], off
	v_subrev_u32_e32 v251, s12, v198
	v_add_u32_e32 v198, 0x30040, v190
	v_ashrrev_i32_e32 v199, 31, v198
	v_lshlrev_b64 v[198:199], 1, v[198:199]
	v_readfirstlane_b32 s24, v217
	v_lshl_add_u64 v[190:191], s[12:13], 0, v[198:199]
	s_mov_b32 m0, s24
	v_lshl_add_u64 v[192:193], s[14:15], 0, v[192:193]
	global_load_lds_dwordx4 v[190:191], off
	v_subrev_u32_e32 v250, s12, v190
	v_add_u32_e32 v190, 0x8000, v195
	s_nop 0
	v_readfirstlane_b32 s24, v190
	s_mov_b32 m0, s24
	s_nop 0
	global_load_lds_dwordx4 v[192:193], off
	v_lshl_add_u64 v[192:193], s[14:15], 0, v[196:197]
	v_add_u32_e32 v196, 0xa000, v195
	s_nop 0
	v_readfirstlane_b32 s24, v196
	v_add_u32_e32 v196, 0xc000, v195
	s_mov_b32 m0, s24
	v_readfirstlane_b32 s24, v196
	v_add_u32_e32 v195, 0xe000, v195
	global_load_lds_dwordx4 v[192:193], off
	v_lshl_add_u64 v[192:193], s[14:15], 0, v[200:201]
	s_mov_b32 m0, s24
	v_readfirstlane_b32 s24, v195
	global_load_lds_dwordx4 v[192:193], off
	v_lshl_add_u64 v[192:193], s[14:15], 0, v[198:199]
	s_mov_b32 m0, s24
	s_nop 0
	global_load_lds_dwordx4 v[192:193], off
	s_add_u32 s98, s12, 0x80
	s_addc_u32 s99, s13, 0
	s_add_u32 s100, s14, 0x80
	s_addc_u32 s101, s15, 0
	v_readfirstlane_b32 s26, v148
	s_nop 0
	s_nop 0
	v_add_u32_e32 v153, s23, v151
	v_add_u32_e32 v194, v153, v150
	ds_read_b128 v[154:157], v194 offset:32768
	ds_read_b128 v[158:161], v194 offset:34816
	ds_read_b128 v[162:165], v194 offset:36864
	ds_read_b128 v[166:169], v194 offset:38912
	v_add_u32_e32 v153, v153, v149
	ds_read_b128 v[170:173], v153
	ds_read_b128 v[174:177], v153 offset:2048
	ds_read_b128 v[178:181], v153 offset:4096
	ds_read_b128 v[182:185], v153 offset:6144
	ds_read_b128 v[186:189], v153 offset:8192
	s_branch .Lg_rot874_main
